# hoist compiler vmcnt(0) out of both GEMM K-loops (main and half-tile variant) to the loop preheaders
# speedup vs baseline: 1.0575x; 1.0123x over previous
.LBB0_365:
	s_add_i32 s9, s46, -2
	s_add_u32 s14, s12, 0x100
	s_addc_u32 s15, s13, 0
	s_add_u32 s0, s10, 0x80
	v_cmp_eq_u32_e32 vcc, 0, v0
	s_addc_u32 s1, s11, 0
	s_cbranch_vccnz .LBB0_369
	s_add_u32 s10, s10, 0x80
	s_addc_u32 s11, s11, 0
	s_add_u32 s22, s12, 0x100
	v_mov_b32_e32 v40, 0
	s_addc_u32 s23, s13, 0
	s_mov_b32 s12, 0
	v_mov_b32_e32 v41, v40
	v_mov_b32_e32 v42, v40
	v_mov_b32_e32 v43, v40
	v_mov_b32_e32 v48, v40
	v_mov_b32_e32 v49, v40
	v_mov_b32_e32 v50, v40
	v_mov_b32_e32 v51, v40
	v_mov_b32_e32 v74, v40
	v_mov_b32_e32 v75, v40
	v_mov_b32_e32 v76, v40
	v_mov_b32_e32 v77, v40
	v_mov_b32_e32 v86, v40
	v_mov_b32_e32 v87, v40
	v_mov_b32_e32 v88, v40
	v_mov_b32_e32 v89, v40
	v_mov_b32_e32 v98, v40
	v_mov_b32_e32 v99, v40
	v_mov_b32_e32 v100, v40
	v_mov_b32_e32 v101, v40
	v_mov_b32_e32 v102, v40
	v_mov_b32_e32 v103, v40
	v_mov_b32_e32 v104, v40
	v_mov_b32_e32 v105, v40
	v_mov_b32_e32 v114, v40
	v_mov_b32_e32 v115, v40
	v_mov_b32_e32 v116, v40
	v_mov_b32_e32 v117, v40
	v_mov_b32_e32 v118, v40
	v_mov_b32_e32 v119, v40
	v_mov_b32_e32 v120, v40
	v_mov_b32_e32 v121, v40
	v_mov_b32_e32 v56, v40
	v_mov_b32_e32 v57, v40
	v_mov_b32_e32 v58, v40
	v_mov_b32_e32 v59, v40
	v_mov_b32_e32 v66, v40
	v_mov_b32_e32 v67, v40
	v_mov_b32_e32 v68, v40
	v_mov_b32_e32 v69, v40
	v_mov_b32_e32 v90, v40
	v_mov_b32_e32 v91, v40
	v_mov_b32_e32 v92, v40
	v_mov_b32_e32 v93, v40
	v_mov_b32_e32 v94, v40
	v_mov_b32_e32 v95, v40
	v_mov_b32_e32 v96, v40
	v_mov_b32_e32 v97, v40
	v_mov_b32_e32 v106, v40
	v_mov_b32_e32 v107, v40
	v_mov_b32_e32 v108, v40
	v_mov_b32_e32 v109, v40
	v_mov_b32_e32 v110, v40
	v_mov_b32_e32 v111, v40
	v_mov_b32_e32 v112, v40
	v_mov_b32_e32 v113, v40
	v_mov_b32_e32 v122, v40
	v_mov_b32_e32 v123, v40
	v_mov_b32_e32 v124, v40
	v_mov_b32_e32 v125, v40
	v_mov_b32_e32 v126, v40
	v_mov_b32_e32 v127, v40
	v_mov_b32_e32 v128, v40
	v_mov_b32_e32 v129, v40
	s_waitcnt vmcnt(0)
.LBB0_367:
	s_add_i32 s25, s12, 2
	s_add_u32 s41, s10, 0x80
	s_addc_u32 s13, s11, 0
	s_add_i32 s47, 16, 0x10000
	v_add_u32_e32 v12, s47, v246
	ds_read_b128 v[0:3], v12
	ds_read_b128 v[4:7], v12 offset:1024
	ds_read_b128 v[8:11], v12 offset:2048
	ds_read_b128 v[12:15], v12 offset:3072
	s_cmp_eq_u32 s9, s12
	s_cselect_b32 s12, s50, s41
	s_cselect_b32 s13, s51, s13
	s_cselect_b32 s61, s27, s23
	s_cselect_b32 s60, s26, s22
	v_add_u32_e32 v64, 16, v249
	v_lshl_add_u64 v[60:61], s[10:11], 0, v[226:227]
	s_add_i32 m0, s78, 0xc000
	ds_read_b128 v[16:19], v64
	ds_read_b128 v[20:23], v64 offset:1024
	ds_read_b128 v[24:27], v64 offset:2048
	ds_read_b128 v[28:31], v64 offset:3072
	ds_read_b128 v[32:35], v64 offset:4096
	ds_read_b128 v[36:39], v64 offset:5120
	ds_read_b128 v[44:47], v64 offset:6144
	ds_read_b128 v[52:55], v64 offset:7168
	global_load_lds_dwordx4 v[60:61], off
	v_lshl_add_u64 v[60:61], s[10:11], 0, v[228:229]
	s_add_i32 m0, s78, 0xe000
	s_nop 0
	global_load_lds_dwordx4 v[60:61], off
	s_waitcnt lgkmcnt(8)
	s_barrier
	s_waitcnt lgkmcnt(0)
	s_setprio 1
	s_waitcnt lgkmcnt(0)
	v_mfma_f32_16x16x32_bf16 v[60:63], v[0:3], v[16:19], v[126:129]
	v_mfma_f32_16x16x32_bf16 v[78:81], v[0:3], v[24:27], v[110:113]
	v_mfma_f32_16x16x32_bf16 v[94:97], v[0:3], v[32:35], v[94:97]
	v_mfma_f32_16x16x32_bf16 v[90:93], v[8:11], v[32:35], v[90:93]
	v_mfma_f32_16x16x32_bf16 v[0:3], v[0:3], v[44:47], v[66:69]
	v_mfma_f32_16x16x32_bf16 v[60:63], v[4:7], v[20:23], v[60:63]
	v_mfma_f32_16x16x32_bf16 v[70:73], v[8:11], v[16:19], v[122:125]
	v_mfma_f32_16x16x32_bf16 v[78:81], v[4:7], v[28:31], v[78:81]
	v_mfma_f32_16x16x32_bf16 v[82:85], v[8:11], v[24:27], v[106:109]
	v_mfma_f32_16x16x32_bf16 v[94:97], v[4:7], v[36:39], v[94:97]
	v_mfma_f32_16x16x32_bf16 v[90:93], v[12:15], v[36:39], v[90:93]
	v_mfma_f32_16x16x32_bf16 v[0:3], v[4:7], v[52:55], v[0:3]
	v_mfma_f32_16x16x32_bf16 v[4:7], v[8:11], v[44:47], v[56:59]
	v_mfma_f32_16x16x32_bf16 v[70:73], v[12:15], v[20:23], v[70:73]
	v_mfma_f32_16x16x32_bf16 v[82:85], v[12:15], v[28:31], v[82:85]
	v_mfma_f32_16x16x32_bf16 v[4:7], v[12:15], v[52:55], v[4:7]
	s_setprio 0
	s_barrier
	s_add_i32 s41, 16, 0x14000
	s_add_i32 s47, s47, s88
	v_add_u32_e32 v66, s41, v246
	v_lshl_add_u64 v[146:147], s[60:61], 0, v[224:225]
	s_mov_b32 m0, s47
	ds_read_b128 v[8:11], v66
	ds_read_b128 v[12:15], v66 offset:1024
	ds_read_b128 v[56:59], v66 offset:2048
	ds_read_b128 v[66:69], v66 offset:3072
	global_load_lds_dwordx4 v[146:147], off
	v_lshl_add_u64 v[148:149], v[146:147], 0, s[42:43]
	s_add_i32 m0, s47, 0x2000
	s_nop 0
	global_load_lds_dwordx4 v[148:149], off
	s_barrier
	s_waitcnt lgkmcnt(0)
	s_setprio 1
	s_waitcnt lgkmcnt(0)
	v_mfma_f32_16x16x32_bf16 v[106:109], v[8:11], v[16:19], v[118:121]
	v_mfma_f32_16x16x32_bf16 v[16:19], v[56:59], v[16:19], v[114:117]
	v_mfma_f32_16x16x32_bf16 v[118:121], v[12:15], v[20:23], v[106:109]
	v_mfma_f32_16x16x32_bf16 v[16:19], v[66:69], v[20:23], v[16:19]
	v_mfma_f32_16x16x32_bf16 v[20:23], v[8:11], v[24:27], v[102:105]
	v_mfma_f32_16x16x32_bf16 v[24:27], v[56:59], v[24:27], v[98:101]
	v_mfma_f32_16x16x32_bf16 v[20:23], v[12:15], v[28:31], v[20:23]
	v_mfma_f32_16x16x32_bf16 v[24:27], v[66:69], v[28:31], v[24:27]
	v_mfma_f32_16x16x32_bf16 v[28:31], v[8:11], v[32:35], v[86:89]
	v_mfma_f32_16x16x32_bf16 v[8:11], v[8:11], v[44:47], v[48:51]
	v_mfma_f32_16x16x32_bf16 v[28:31], v[12:15], v[36:39], v[28:31]
	v_mfma_f32_16x16x32_bf16 v[32:35], v[56:59], v[32:35], v[74:77]
	v_mfma_f32_16x16x32_bf16 v[8:11], v[12:15], v[52:55], v[8:11]
	v_mfma_f32_16x16x32_bf16 v[12:15], v[56:59], v[44:47], v[40:43]
	v_mfma_f32_16x16x32_bf16 v[32:35], v[66:69], v[36:39], v[32:35]
	v_mfma_f32_16x16x32_bf16 v[12:15], v[66:69], v[52:55], v[12:15]
	s_setprio 0
	s_mov_b32 m0, s78
	v_lshl_add_u64 v[150:151], s[12:13], 0, v[224:225]
	s_barrier
	global_load_lds_dwordx4 v[150:151], off
	v_lshl_add_u64 v[152:153], v[150:151], 0, s[42:43]
	s_mov_b32 m0, s36
	s_nop 0
	global_load_lds_dwordx4 v[152:153], off
	s_barrier
	s_waitcnt lgkmcnt(0)
	s_barrier
	s_add_u32 s60, s60, s44
	s_addc_u32 s61, s61, 0
	s_add_i32 s41, s41, s88
	v_lshl_add_u64 v[154:155], s[60:61], 0, v[224:225]
	s_mov_b32 m0, s41
	v_lshl_add_u64 v[156:157], v[154:155], 0, s[42:43]
	global_load_lds_dwordx4 v[154:155], off
	s_add_i32 m0, s41, 0x2000
	s_add_i32 s41, 16, 0x18000
	global_load_lds_dwordx4 v[156:157], off
	v_add_u32_e32 v48, s41, v246
	s_waitcnt vmcnt(6)
	s_barrier
	s_barrier
	ds_read_b128 v[36:39], v48
	ds_read_b128 v[40:43], v48 offset:1024
	ds_read_b128 v[44:47], v48 offset:2048
	ds_read_b128 v[48:51], v48 offset:3072
	s_add_u32 s12, s12, s44
	s_addc_u32 s13, s13, 0
	s_mov_b32 m0, s37
	v_lshl_add_u64 v[56:57], s[12:13], 0, v[224:225]
	ds_read_b128 v[52:55], v64 offset:32768
	ds_read_b128 v[74:77], v64 offset:33792
	ds_read_b128 v[86:89], v64 offset:34816
	ds_read_b128 v[98:101], v64 offset:35840
	ds_read_b128 v[130:133], v64 offset:36864
	ds_read_b128 v[134:137], v64 offset:37888
	ds_read_b128 v[138:141], v64 offset:38912
	ds_read_b128 v[142:145], v64 offset:39936
	global_load_lds_dwordx4 v[56:57], off
	v_lshl_add_u64 v[56:57], v[56:57], 0, s[42:43]
	s_mov_b32 m0, s82
	s_nop 0
	global_load_lds_dwordx4 v[56:57], off
	s_waitcnt lgkmcnt(8)
	s_barrier
	s_waitcnt lgkmcnt(0)
	s_setprio 1
	s_waitcnt lgkmcnt(0)
	v_mfma_f32_16x16x32_bf16 v[56:59], v[36:39], v[52:55], v[60:63]
	v_mfma_f32_16x16x32_bf16 v[126:129], v[40:43], v[74:77], v[56:59]
	v_mfma_f32_16x16x32_bf16 v[56:59], v[44:47], v[52:55], v[70:73]
	v_mfma_f32_16x16x32_bf16 v[122:125], v[48:51], v[74:77], v[56:59]
	v_mfma_f32_16x16x32_bf16 v[56:59], v[36:39], v[86:89], v[78:81]
	v_mfma_f32_16x16x32_bf16 v[110:113], v[40:43], v[98:101], v[56:59]
	v_mfma_f32_16x16x32_bf16 v[56:59], v[44:47], v[86:89], v[82:85]
	v_mfma_f32_16x16x32_bf16 v[106:109], v[48:51], v[98:101], v[56:59]
	v_mfma_f32_16x16x32_bf16 v[56:59], v[36:39], v[130:133], v[94:97]
	v_mfma_f32_16x16x32_bf16 v[0:3], v[36:39], v[138:141], v[0:3]
	v_mfma_f32_16x16x32_bf16 v[94:97], v[40:43], v[134:137], v[56:59]
	v_mfma_f32_16x16x32_bf16 v[56:59], v[44:47], v[130:133], v[90:93]
	v_mfma_f32_16x16x32_bf16 v[66:69], v[40:43], v[142:145], v[0:3]
	v_mfma_f32_16x16x32_bf16 v[0:3], v[44:47], v[138:141], v[4:7]
	v_mfma_f32_16x16x32_bf16 v[90:93], v[48:51], v[134:137], v[56:59]
	v_mfma_f32_16x16x32_bf16 v[56:59], v[48:51], v[142:145], v[0:3]
	s_setprio 0
	s_barrier
	s_add_i32 s12, 16, 0x1c000
	s_add_i32 s13, s41, s88
	v_add_u32_e32 v40, s12, v246
	v_lshl_add_u64 v[44:45], v[146:147], 0, s[62:63]
	s_mov_b32 m0, s13
	ds_read_b128 v[0:3], v40
	ds_read_b128 v[4:7], v40 offset:1024
	ds_read_b128 v[36:39], v40 offset:2048
	ds_read_b128 v[40:43], v40 offset:3072
	global_load_lds_dwordx4 v[44:45], off
	v_lshl_add_u64 v[44:45], v[148:149], 0, s[62:63]
	s_add_i32 m0, s13, 0x2000
	s_nop 0
	global_load_lds_dwordx4 v[44:45], off
	s_barrier
	s_waitcnt lgkmcnt(0)
	s_setprio 1
	s_waitcnt lgkmcnt(0)
	v_mfma_f32_16x16x32_bf16 v[16:19], v[36:39], v[52:55], v[16:19]
	v_mfma_f32_16x16x32_bf16 v[114:117], v[40:43], v[74:77], v[16:19]
	v_mfma_f32_16x16x32_bf16 v[16:19], v[0:3], v[86:89], v[20:23]
	v_mfma_f32_16x16x32_bf16 v[102:105], v[4:7], v[98:101], v[16:19]
	v_mfma_f32_16x16x32_bf16 v[16:19], v[36:39], v[86:89], v[24:27]
	v_mfma_f32_16x16x32_bf16 v[44:47], v[0:3], v[52:55], v[118:121]
	v_mfma_f32_16x16x32_bf16 v[98:101], v[40:43], v[98:101], v[16:19]
	v_mfma_f32_16x16x32_bf16 v[16:19], v[0:3], v[130:133], v[28:31]
	v_mfma_f32_16x16x32_bf16 v[0:3], v[0:3], v[138:141], v[8:11]
	v_mfma_f32_16x16x32_bf16 v[86:89], v[4:7], v[134:137], v[16:19]
	v_mfma_f32_16x16x32_bf16 v[16:19], v[36:39], v[130:133], v[32:35]
	v_mfma_f32_16x16x32_bf16 v[48:51], v[4:7], v[142:145], v[0:3]
	v_mfma_f32_16x16x32_bf16 v[0:3], v[36:39], v[138:141], v[12:15]
	v_mfma_f32_16x16x32_bf16 v[118:121], v[4:7], v[74:77], v[44:47]
	v_mfma_f32_16x16x32_bf16 v[74:77], v[40:43], v[134:137], v[16:19]
	v_mfma_f32_16x16x32_bf16 v[40:43], v[40:43], v[142:145], v[0:3]
	s_setprio 0
	s_mov_b32 m0, s87
	s_nop 2
	v_lshl_add_u64 v[0:1], v[150:151], 0, s[62:63]
	s_barrier
	global_load_lds_dwordx4 v[0:1], off
	v_lshl_add_u64 v[0:1], v[152:153], 0, s[62:63]
	s_mov_b32 m0, s52
	s_nop 0
	global_load_lds_dwordx4 v[0:1], off
	s_barrier
	s_waitcnt lgkmcnt(0)
	s_barrier
	s_add_i32 s12, s12, s88
	v_lshl_add_u64 v[0:1], v[154:155], 0, s[62:63]
	s_mov_b32 m0, s12
	s_nop 0
	global_load_lds_dwordx4 v[0:1], off
	v_lshl_add_u64 v[0:1], v[156:157], 0, s[62:63]
	s_add_i32 m0, s12, 0x2000
	s_add_u32 s10, s10, 0x100
	global_load_lds_dwordx4 v[0:1], off
	s_addc_u32 s11, s11, 0
	s_waitcnt vmcnt(6)
	s_add_u32 s22, s22, 0x100
	s_addc_u32 s23, s23, 0
	s_cmp_ge_i32 s25, s46
	s_mov_b32 s12, s25
	s_barrier
	s_barrier
	s_cbranch_scc0 .LBB0_367
	s_mov_b64 s[10:11], 0
	s_branch .LBB0_370

; DI void gemm_phase(char* shm_, const bf16* __restrict__ Ag, const bf16* __restrict__ Btg, int K, int ntm, int ntn, const Epi& E, int split, int toff, int shalf) {
;     ...
;     if (hl) { KLOOP(1) } else { KLOOP(0) }
;     ...
;     epilogue(acc, E, pm * BM, pn * BM, wr, wc, fr, fq, at);
;     if (!has_next) break;
;     _Pragma("unroll") for (int a = 0; a < 2; ++a) _Pragma("unroll") for (int b = 0; b < 2; ++b) _Pragma("unroll") for (int m = 0; m < 4; ++m) _Pragma("unroll") for (int n = 0; n < 2; ++n) acc[a][b][m][n] = (f32x4){0.f, 0.f, 0.f, 0.f};
.LBB0_370:
	v_mov_b32_e32 v85, 0
	s_and_b64 vcc, exec, s[10:11]
	v_mov_b32_e32 v84, v85
	v_mov_b32_e32 v83, v85
	v_mov_b32_e32 v82, v85
	v_mov_b32_e32 v81, v85
	v_mov_b32_e32 v80, v85
	v_mov_b32_e32 v79, v85
	v_mov_b32_e32 v78, v85
	v_mov_b32_e32 v55, v85
	v_mov_b32_e32 v54, v85
	v_mov_b32_e32 v53, v85
	v_mov_b32_e32 v52, v85
	v_mov_b32_e32 v47, v85
	v_mov_b32_e32 v46, v85
	v_mov_b32_e32 v45, v85
	v_mov_b32_e32 v44, v85
	v_mov_b32_e32 v31, v85
	v_mov_b32_e32 v30, v85
	v_mov_b32_e32 v29, v85
	v_mov_b32_e32 v28, v85
	v_mov_b32_e32 v27, v85
	v_mov_b32_e32 v26, v85
	v_mov_b32_e32 v25, v85
	v_mov_b32_e32 v24, v85
	v_mov_b32_e32 v15, v85
	v_mov_b32_e32 v14, v85
	v_mov_b32_e32 v13, v85
	v_mov_b32_e32 v12, v85
	v_mov_b32_e32 v11, v85
	v_mov_b32_e32 v10, v85
	v_mov_b32_e32 v9, v85
	v_mov_b32_e32 v8, v85
	v_mov_b32_e32 v73, v85
	v_mov_b32_e32 v72, v85
	v_mov_b32_e32 v71, v85
	v_mov_b32_e32 v70, v85
	v_mov_b32_e32 v63, v85
	v_mov_b32_e32 v62, v85
	v_mov_b32_e32 v61, v85
	v_mov_b32_e32 v60, v85
	v_mov_b32_e32 v39, v85
	v_mov_b32_e32 v38, v85
	v_mov_b32_e32 v37, v85
	v_mov_b32_e32 v36, v85
	v_mov_b32_e32 v35, v85
	v_mov_b32_e32 v34, v85
	v_mov_b32_e32 v33, v85
	v_mov_b32_e32 v32, v85
	v_mov_b32_e32 v23, v85
	v_mov_b32_e32 v22, v85
	v_mov_b32_e32 v21, v85
	v_mov_b32_e32 v20, v85
	v_mov_b32_e32 v19, v85
	v_mov_b32_e32 v18, v85
	v_mov_b32_e32 v17, v85
	v_mov_b32_e32 v16, v85
	v_mov_b32_e32 v7, v85
	v_mov_b32_e32 v6, v85
	v_mov_b32_e32 v5, v85
	v_mov_b32_e32 v4, v85
	v_mov_b32_e32 v3, v85
	v_mov_b32_e32 v2, v85
	v_mov_b32_e32 v1, v85
	v_mov_b32_e32 v0, v85
	s_cbranch_vccz .LBB0_373
	v_mov_b32_e32 v0, 0
	s_mov_b32 s10, 0
	v_mov_b32_e32 v1, v0
	v_mov_b32_e32 v2, v0
	v_mov_b32_e32 v3, v0
	v_mov_b32_e32 v4, v0
	v_mov_b32_e32 v5, v0
	v_mov_b32_e32 v6, v0
	v_mov_b32_e32 v7, v0
	v_mov_b32_e32 v16, v0
	v_mov_b32_e32 v17, v0
	v_mov_b32_e32 v18, v0
	v_mov_b32_e32 v19, v0
	v_mov_b32_e32 v20, v0
	v_mov_b32_e32 v21, v0
	v_mov_b32_e32 v22, v0
	v_mov_b32_e32 v23, v0
	v_mov_b32_e32 v32, v0
	v_mov_b32_e32 v33, v0
	v_mov_b32_e32 v34, v0
	v_mov_b32_e32 v35, v0
	v_mov_b32_e32 v36, v0
	v_mov_b32_e32 v37, v0
	v_mov_b32_e32 v38, v0
	v_mov_b32_e32 v39, v0
	v_mov_b32_e32 v60, v0
	v_mov_b32_e32 v61, v0
	v_mov_b32_e32 v62, v0
	v_mov_b32_e32 v63, v0
	v_mov_b32_e32 v70, v0
	v_mov_b32_e32 v71, v0
	v_mov_b32_e32 v72, v0
	v_mov_b32_e32 v73, v0
	v_mov_b32_e32 v8, v0
	v_mov_b32_e32 v9, v0
	v_mov_b32_e32 v10, v0
	v_mov_b32_e32 v11, v0
	v_mov_b32_e32 v12, v0
	v_mov_b32_e32 v13, v0
	v_mov_b32_e32 v14, v0
	v_mov_b32_e32 v15, v0
	v_mov_b32_e32 v24, v0
	v_mov_b32_e32 v25, v0
	v_mov_b32_e32 v26, v0
	v_mov_b32_e32 v27, v0
	v_mov_b32_e32 v28, v0
	v_mov_b32_e32 v29, v0
	v_mov_b32_e32 v30, v0
	v_mov_b32_e32 v31, v0
	v_mov_b32_e32 v44, v0
	v_mov_b32_e32 v45, v0
	v_mov_b32_e32 v46, v0
	v_mov_b32_e32 v47, v0
	v_mov_b32_e32 v52, v0
	v_mov_b32_e32 v53, v0
	v_mov_b32_e32 v54, v0
	v_mov_b32_e32 v55, v0
	v_mov_b32_e32 v78, v0
	v_mov_b32_e32 v79, v0
	v_mov_b32_e32 v80, v0
	v_mov_b32_e32 v81, v0
	v_mov_b32_e32 v82, v0
	v_mov_b32_e32 v83, v0
	v_mov_b32_e32 v84, v0
	v_mov_b32_e32 v85, v0
	v_mov_b32_e32 v40, v0
	v_mov_b32_e32 v41, v0
	v_mov_b32_e32 v42, v0
	v_mov_b32_e32 v43, v0
	v_mov_b32_e32 v48, v0
	v_mov_b32_e32 v49, v0
	v_mov_b32_e32 v50, v0
	v_mov_b32_e32 v51, v0
	v_mov_b32_e32 v74, v0
	v_mov_b32_e32 v75, v0
	v_mov_b32_e32 v76, v0
	v_mov_b32_e32 v77, v0
	v_mov_b32_e32 v86, v0
	v_mov_b32_e32 v87, v0
	v_mov_b32_e32 v88, v0
	v_mov_b32_e32 v89, v0
	v_mov_b32_e32 v98, v0
	v_mov_b32_e32 v99, v0
	v_mov_b32_e32 v100, v0
	v_mov_b32_e32 v101, v0
	v_mov_b32_e32 v102, v0
	v_mov_b32_e32 v103, v0
	v_mov_b32_e32 v104, v0
	v_mov_b32_e32 v105, v0
	v_mov_b32_e32 v114, v0
	v_mov_b32_e32 v115, v0
	v_mov_b32_e32 v116, v0
	v_mov_b32_e32 v117, v0
	v_mov_b32_e32 v118, v0
	v_mov_b32_e32 v119, v0
	v_mov_b32_e32 v120, v0
	v_mov_b32_e32 v121, v0
	v_mov_b32_e32 v56, v0
	v_mov_b32_e32 v57, v0
	v_mov_b32_e32 v58, v0
	v_mov_b32_e32 v59, v0
	v_mov_b32_e32 v66, v0
	v_mov_b32_e32 v67, v0
	v_mov_b32_e32 v68, v0
	v_mov_b32_e32 v69, v0
	v_mov_b32_e32 v90, v0
	v_mov_b32_e32 v91, v0
	v_mov_b32_e32 v92, v0
	v_mov_b32_e32 v93, v0
	v_mov_b32_e32 v94, v0
	v_mov_b32_e32 v95, v0
	v_mov_b32_e32 v96, v0
	v_mov_b32_e32 v97, v0
	v_mov_b32_e32 v106, v0
	v_mov_b32_e32 v107, v0
	v_mov_b32_e32 v108, v0
	v_mov_b32_e32 v109, v0
	v_mov_b32_e32 v110, v0
	v_mov_b32_e32 v111, v0
	v_mov_b32_e32 v112, v0
	v_mov_b32_e32 v113, v0
	v_mov_b32_e32 v122, v0
	v_mov_b32_e32 v123, v0
	v_mov_b32_e32 v124, v0
	v_mov_b32_e32 v125, v0
	v_mov_b32_e32 v126, v0
	v_mov_b32_e32 v127, v0
	v_mov_b32_e32 v128, v0
	v_mov_b32_e32 v129, v0
	s_waitcnt vmcnt(0) lgkmcnt(0)
.LBB0_372:
	s_add_i32 s22, s10, 2
	s_add_u32 s12, s0, 0x80
	s_addc_u32 s11, s1, 0
	s_add_i32 s23, 16, 0x10000
	v_add_u32_e32 v64, s23, v246
	ds_read_b128 v[130:133], v64
	ds_read_b128 v[134:137], v64 offset:1024
	ds_read_b128 v[138:141], v64 offset:2048
	ds_read_b128 v[142:145], v64 offset:3072
	s_cmp_eq_u32 s9, s10
	s_cselect_b32 s10, s50, s12
	s_cselect_b32 s11, s51, s11
	s_cselect_b32 s13, s27, s15
	s_cselect_b32 s12, s26, s14
	v_add_u32_e32 v64, 16, v249
	v_lshl_add_u64 v[178:179], s[0:1], 0, v[226:227]
	s_add_i32 m0, s78, 0xc000
	ds_read_b128 v[146:149], v64
	ds_read_b128 v[150:153], v64 offset:1024
	ds_read_b128 v[154:157], v64 offset:2048
	ds_read_b128 v[158:161], v64 offset:3072
	ds_read_b128 v[162:165], v64 offset:4096
	ds_read_b128 v[166:169], v64 offset:5120
	ds_read_b128 v[170:173], v64 offset:6144
	ds_read_b128 v[174:177], v64 offset:7168
	global_load_lds_dwordx4 v[178:179], off
	v_lshl_add_u64 v[178:179], s[0:1], 0, v[228:229]
	s_add_i32 m0, s78, 0xe000
	s_nop 0
	global_load_lds_dwordx4 v[178:179], off
	s_waitcnt lgkmcnt(8)
	s_barrier
	s_waitcnt lgkmcnt(0)
	s_setprio 1
	s_waitcnt lgkmcnt(0)
	v_mfma_f32_16x16x32_bf16 v[126:129], v[130:133], v[146:149], v[126:129]
	v_mfma_f32_16x16x32_bf16 v[122:125], v[138:141], v[146:149], v[122:125]
	v_mfma_f32_16x16x32_bf16 v[110:113], v[130:133], v[154:157], v[110:113]
	v_mfma_f32_16x16x32_bf16 v[106:109], v[138:141], v[154:157], v[106:109]
	v_mfma_f32_16x16x32_bf16 v[94:97], v[130:133], v[162:165], v[94:97]
	v_mfma_f32_16x16x32_bf16 v[90:93], v[138:141], v[162:165], v[90:93]
	v_mfma_f32_16x16x32_bf16 v[66:69], v[130:133], v[170:173], v[66:69]
	v_mfma_f32_16x16x32_bf16 v[56:59], v[138:141], v[170:173], v[56:59]
	v_mfma_f32_16x16x32_bf16 v[126:129], v[134:137], v[150:153], v[126:129]
	v_mfma_f32_16x16x32_bf16 v[122:125], v[142:145], v[150:153], v[122:125]
	v_mfma_f32_16x16x32_bf16 v[110:113], v[134:137], v[158:161], v[110:113]
	v_mfma_f32_16x16x32_bf16 v[106:109], v[142:145], v[158:161], v[106:109]
	v_mfma_f32_16x16x32_bf16 v[94:97], v[134:137], v[166:169], v[94:97]
	v_mfma_f32_16x16x32_bf16 v[90:93], v[142:145], v[166:169], v[90:93]
	v_mfma_f32_16x16x32_bf16 v[66:69], v[134:137], v[174:177], v[66:69]
	v_mfma_f32_16x16x32_bf16 v[56:59], v[142:145], v[174:177], v[56:59]
	s_setprio 0
	s_barrier
	s_add_i32 s25, 16, 0x14000
	s_add_i32 s23, s23, s88
	v_add_u32_e32 v190, s25, v246
	v_lshl_add_u64 v[194:195], s[12:13], 0, v[224:225]
	s_mov_b32 m0, s23
	ds_read_b128 v[178:181], v190
	ds_read_b128 v[182:185], v190 offset:1024
	ds_read_b128 v[186:189], v190 offset:2048
	ds_read_b128 v[190:193], v190 offset:3072
	global_load_lds_dwordx4 v[194:195], off
	v_lshl_add_u64 v[196:197], v[194:195], 0, s[42:43]
	s_add_i32 m0, s23, 0x2000
	s_nop 0
	global_load_lds_dwordx4 v[196:197], off
	s_barrier
	s_waitcnt lgkmcnt(0)
	s_setprio 1
	s_waitcnt lgkmcnt(0)
	v_mfma_f32_16x16x32_bf16 v[118:121], v[178:181], v[146:149], v[118:121]
	v_mfma_f32_16x16x32_bf16 v[114:117], v[186:189], v[146:149], v[114:117]
	v_mfma_f32_16x16x32_bf16 v[102:105], v[178:181], v[154:157], v[102:105]
	v_mfma_f32_16x16x32_bf16 v[98:101], v[186:189], v[154:157], v[98:101]
	v_mfma_f32_16x16x32_bf16 v[86:89], v[178:181], v[162:165], v[86:89]
	v_mfma_f32_16x16x32_bf16 v[74:77], v[186:189], v[162:165], v[74:77]
	v_mfma_f32_16x16x32_bf16 v[48:51], v[178:181], v[170:173], v[48:51]
	v_mfma_f32_16x16x32_bf16 v[40:43], v[186:189], v[170:173], v[40:43]
	v_mfma_f32_16x16x32_bf16 v[118:121], v[182:185], v[150:153], v[118:121]
	v_mfma_f32_16x16x32_bf16 v[114:117], v[190:193], v[150:153], v[114:117]
	v_mfma_f32_16x16x32_bf16 v[102:105], v[182:185], v[158:161], v[102:105]
	v_mfma_f32_16x16x32_bf16 v[98:101], v[190:193], v[158:161], v[98:101]
	v_mfma_f32_16x16x32_bf16 v[86:89], v[182:185], v[166:169], v[86:89]
	v_mfma_f32_16x16x32_bf16 v[74:77], v[190:193], v[166:169], v[74:77]
	v_mfma_f32_16x16x32_bf16 v[48:51], v[182:185], v[174:177], v[48:51]
	v_mfma_f32_16x16x32_bf16 v[40:43], v[190:193], v[174:177], v[40:43]
	s_setprio 0
	s_mov_b32 m0, s78
	v_lshl_add_u64 v[198:199], s[10:11], 0, v[224:225]
	s_barrier
	ds_read_b128 v[146:149], v64 offset:16384
	ds_read_b128 v[150:153], v64 offset:17408
	ds_read_b128 v[154:157], v64 offset:18432
	ds_read_b128 v[158:161], v64 offset:19456
	ds_read_b128 v[162:165], v64 offset:20480
	ds_read_b128 v[166:169], v64 offset:21504
	ds_read_b128 v[170:173], v64 offset:22528
	ds_read_b128 v[174:177], v64 offset:23552
	global_load_lds_dwordx4 v[198:199], off
	v_lshl_add_u64 v[200:201], v[198:199], 0, s[42:43]
	s_mov_b32 m0, s36
	s_nop 0
	global_load_lds_dwordx4 v[200:201], off
	s_barrier
	s_waitcnt lgkmcnt(0)
	s_setprio 1
	s_waitcnt lgkmcnt(0)
	v_mfma_f32_16x16x32_bf16 v[82:85], v[130:133], v[146:149], v[82:85]
	v_mfma_f32_16x16x32_bf16 v[78:81], v[138:141], v[146:149], v[78:81]
	v_mfma_f32_16x16x32_bf16 v[52:55], v[130:133], v[154:157], v[52:55]
	v_mfma_f32_16x16x32_bf16 v[44:47], v[138:141], v[154:157], v[44:47]
	v_mfma_f32_16x16x32_bf16 v[28:31], v[130:133], v[162:165], v[28:31]
	v_mfma_f32_16x16x32_bf16 v[24:27], v[138:141], v[162:165], v[24:27]
	v_mfma_f32_16x16x32_bf16 v[12:15], v[130:133], v[170:173], v[12:15]
	v_mfma_f32_16x16x32_bf16 v[8:11], v[138:141], v[170:173], v[8:11]
	v_mfma_f32_16x16x32_bf16 v[82:85], v[134:137], v[150:153], v[82:85]
	v_mfma_f32_16x16x32_bf16 v[78:81], v[142:145], v[150:153], v[78:81]
	v_mfma_f32_16x16x32_bf16 v[52:55], v[134:137], v[158:161], v[52:55]
	v_mfma_f32_16x16x32_bf16 v[44:47], v[142:145], v[158:161], v[44:47]
	v_mfma_f32_16x16x32_bf16 v[28:31], v[134:137], v[166:169], v[28:31]
	v_mfma_f32_16x16x32_bf16 v[24:27], v[142:145], v[166:169], v[24:27]
	v_mfma_f32_16x16x32_bf16 v[12:15], v[134:137], v[174:177], v[12:15]
	v_mfma_f32_16x16x32_bf16 v[8:11], v[142:145], v[174:177], v[8:11]
	s_setprio 0
	s_barrier
	s_add_u32 s12, s12, s44
	s_addc_u32 s13, s13, 0
	v_lshl_add_u64 v[202:203], s[12:13], 0, v[224:225]
	s_add_i32 s12, s25, s88
	s_mov_b32 m0, s12
	v_lshl_add_u64 v[204:205], v[202:203], 0, s[42:43]
	global_load_lds_dwordx4 v[202:203], off
	s_add_i32 m0, s12, 0x2000
	s_nop 0
	global_load_lds_dwordx4 v[204:205], off
	s_waitcnt vmcnt(6)
	s_barrier
	s_setprio 1
	v_mfma_f32_16x16x32_bf16 v[70:73], v[178:181], v[146:149], v[70:73]
	v_mfma_f32_16x16x32_bf16 v[60:63], v[186:189], v[146:149], v[60:63]
	v_mfma_f32_16x16x32_bf16 v[36:39], v[178:181], v[154:157], v[36:39]
	v_mfma_f32_16x16x32_bf16 v[32:35], v[186:189], v[154:157], v[32:35]
	v_mfma_f32_16x16x32_bf16 v[20:23], v[178:181], v[162:165], v[20:23]
	v_mfma_f32_16x16x32_bf16 v[16:19], v[186:189], v[162:165], v[16:19]
	v_mfma_f32_16x16x32_bf16 v[4:7], v[178:181], v[170:173], v[4:7]
	v_mfma_f32_16x16x32_bf16 v[0:3], v[186:189], v[170:173], v[0:3]
	v_mfma_f32_16x16x32_bf16 v[70:73], v[182:185], v[150:153], v[70:73]
	v_mfma_f32_16x16x32_bf16 v[60:63], v[190:193], v[150:153], v[60:63]
	v_mfma_f32_16x16x32_bf16 v[36:39], v[182:185], v[158:161], v[36:39]
	v_mfma_f32_16x16x32_bf16 v[32:35], v[190:193], v[158:161], v[32:35]
	v_mfma_f32_16x16x32_bf16 v[20:23], v[182:185], v[166:169], v[20:23]
	v_mfma_f32_16x16x32_bf16 v[16:19], v[190:193], v[166:169], v[16:19]
	v_mfma_f32_16x16x32_bf16 v[4:7], v[182:185], v[174:177], v[4:7]
	v_mfma_f32_16x16x32_bf16 v[0:3], v[190:193], v[174:177], v[0:3]
	s_setprio 0
	s_add_i32 s12, 16, 0x18000
	v_add_u32_e32 v142, s12, v246
	s_barrier
	ds_read_b128 v[130:133], v142
	ds_read_b128 v[134:137], v142 offset:1024
	ds_read_b128 v[138:141], v142 offset:2048
	ds_read_b128 v[142:145], v142 offset:3072
	s_add_u32 s10, s10, s44
	s_addc_u32 s11, s11, 0
	s_mov_b32 m0, s37
	v_lshl_add_u64 v[178:179], s[10:11], 0, v[224:225]
	ds_read_b128 v[146:149], v64 offset:32768
	ds_read_b128 v[150:153], v64 offset:33792
	ds_read_b128 v[154:157], v64 offset:34816
	ds_read_b128 v[158:161], v64 offset:35840
	ds_read_b128 v[162:165], v64 offset:36864
	ds_read_b128 v[166:169], v64 offset:37888
	ds_read_b128 v[170:173], v64 offset:38912
	ds_read_b128 v[174:177], v64 offset:39936
	global_load_lds_dwordx4 v[178:179], off
	v_lshl_add_u64 v[178:179], v[178:179], 0, s[42:43]
	s_mov_b32 m0, s82
	s_nop 0
	global_load_lds_dwordx4 v[178:179], off
	s_waitcnt lgkmcnt(8)
	s_barrier
	s_waitcnt lgkmcnt(0)
	s_setprio 1
	s_waitcnt lgkmcnt(0)
	v_mfma_f32_16x16x32_bf16 v[126:129], v[130:133], v[146:149], v[126:129]
	v_mfma_f32_16x16x32_bf16 v[122:125], v[138:141], v[146:149], v[122:125]
	v_mfma_f32_16x16x32_bf16 v[110:113], v[130:133], v[154:157], v[110:113]
	v_mfma_f32_16x16x32_bf16 v[106:109], v[138:141], v[154:157], v[106:109]
	v_mfma_f32_16x16x32_bf16 v[94:97], v[130:133], v[162:165], v[94:97]
	v_mfma_f32_16x16x32_bf16 v[90:93], v[138:141], v[162:165], v[90:93]
	v_mfma_f32_16x16x32_bf16 v[66:69], v[130:133], v[170:173], v[66:69]
	v_mfma_f32_16x16x32_bf16 v[56:59], v[138:141], v[170:173], v[56:59]
	v_mfma_f32_16x16x32_bf16 v[126:129], v[134:137], v[150:153], v[126:129]
	v_mfma_f32_16x16x32_bf16 v[122:125], v[142:145], v[150:153], v[122:125]
	v_mfma_f32_16x16x32_bf16 v[110:113], v[134:137], v[158:161], v[110:113]
	v_mfma_f32_16x16x32_bf16 v[106:109], v[142:145], v[158:161], v[106:109]
	v_mfma_f32_16x16x32_bf16 v[94:97], v[134:137], v[166:169], v[94:97]
	v_mfma_f32_16x16x32_bf16 v[90:93], v[142:145], v[166:169], v[90:93]
	v_mfma_f32_16x16x32_bf16 v[66:69], v[134:137], v[174:177], v[66:69]
	v_mfma_f32_16x16x32_bf16 v[56:59], v[142:145], v[174:177], v[56:59]
	s_setprio 0
	s_barrier
	s_add_i32 s10, 16, 0x1c000
	s_add_i32 s11, s12, s88
	v_add_u32_e32 v190, s10, v246
	v_lshl_add_u64 v[194:195], v[194:195], 0, s[62:63]
	s_mov_b32 m0, s11
	ds_read_b128 v[178:181], v190
	ds_read_b128 v[182:185], v190 offset:1024
	ds_read_b128 v[186:189], v190 offset:2048
	ds_read_b128 v[190:193], v190 offset:3072
	global_load_lds_dwordx4 v[194:195], off
	v_lshl_add_u64 v[194:195], v[196:197], 0, s[62:63]
	s_add_i32 m0, s11, 0x2000
	s_nop 0
	global_load_lds_dwordx4 v[194:195], off
	s_barrier
	s_waitcnt lgkmcnt(0)
	s_setprio 1
	s_waitcnt lgkmcnt(0)
	v_mfma_f32_16x16x32_bf16 v[118:121], v[178:181], v[146:149], v[118:121]
	v_mfma_f32_16x16x32_bf16 v[114:117], v[186:189], v[146:149], v[114:117]
	v_mfma_f32_16x16x32_bf16 v[102:105], v[178:181], v[154:157], v[102:105]
	v_mfma_f32_16x16x32_bf16 v[98:101], v[186:189], v[154:157], v[98:101]
	v_mfma_f32_16x16x32_bf16 v[86:89], v[178:181], v[162:165], v[86:89]
	v_mfma_f32_16x16x32_bf16 v[74:77], v[186:189], v[162:165], v[74:77]
	v_mfma_f32_16x16x32_bf16 v[48:51], v[178:181], v[170:173], v[48:51]
	v_mfma_f32_16x16x32_bf16 v[40:43], v[186:189], v[170:173], v[40:43]
	v_mfma_f32_16x16x32_bf16 v[118:121], v[182:185], v[150:153], v[118:121]
	v_mfma_f32_16x16x32_bf16 v[114:117], v[190:193], v[150:153], v[114:117]
	v_mfma_f32_16x16x32_bf16 v[102:105], v[182:185], v[158:161], v[102:105]
	v_mfma_f32_16x16x32_bf16 v[98:101], v[190:193], v[158:161], v[98:101]
	v_mfma_f32_16x16x32_bf16 v[86:89], v[182:185], v[166:169], v[86:89]
	v_mfma_f32_16x16x32_bf16 v[74:77], v[190:193], v[166:169], v[74:77]
	v_mfma_f32_16x16x32_bf16 v[48:51], v[182:185], v[174:177], v[48:51]
	v_mfma_f32_16x16x32_bf16 v[40:43], v[190:193], v[174:177], v[40:43]
	s_setprio 0
	s_mov_b32 m0, s87
	v_lshl_add_u64 v[194:195], v[198:199], 0, s[62:63]
	s_barrier
	ds_read_b128 v[146:149], v64 offset:49152
	ds_read_b128 v[150:153], v64 offset:50176
	ds_read_b128 v[154:157], v64 offset:51200
	ds_read_b128 v[158:161], v64 offset:52224
	ds_read_b128 v[162:165], v64 offset:53248
	ds_read_b128 v[166:169], v64 offset:54272
	ds_read_b128 v[170:173], v64 offset:55296
	ds_read_b128 v[174:177], v64 offset:56320
	global_load_lds_dwordx4 v[194:195], off
	v_lshl_add_u64 v[194:195], v[200:201], 0, s[62:63]
	s_mov_b32 m0, s52
	s_nop 0
	global_load_lds_dwordx4 v[194:195], off
	s_barrier
	s_waitcnt lgkmcnt(0)
	s_setprio 1
	s_waitcnt lgkmcnt(0)
	v_mfma_f32_16x16x32_bf16 v[82:85], v[130:133], v[146:149], v[82:85]
	v_mfma_f32_16x16x32_bf16 v[78:81], v[138:141], v[146:149], v[78:81]
	v_mfma_f32_16x16x32_bf16 v[52:55], v[130:133], v[154:157], v[52:55]
	v_mfma_f32_16x16x32_bf16 v[44:47], v[138:141], v[154:157], v[44:47]
	v_mfma_f32_16x16x32_bf16 v[28:31], v[130:133], v[162:165], v[28:31]
	v_mfma_f32_16x16x32_bf16 v[24:27], v[138:141], v[162:165], v[24:27]
	v_mfma_f32_16x16x32_bf16 v[12:15], v[130:133], v[170:173], v[12:15]
	v_mfma_f32_16x16x32_bf16 v[8:11], v[138:141], v[170:173], v[8:11]
	v_mfma_f32_16x16x32_bf16 v[82:85], v[134:137], v[150:153], v[82:85]
	v_mfma_f32_16x16x32_bf16 v[78:81], v[142:145], v[150:153], v[78:81]
	v_mfma_f32_16x16x32_bf16 v[52:55], v[134:137], v[158:161], v[52:55]
	v_mfma_f32_16x16x32_bf16 v[44:47], v[142:145], v[158:161], v[44:47]
	v_mfma_f32_16x16x32_bf16 v[28:31], v[134:137], v[166:169], v[28:31]
	v_mfma_f32_16x16x32_bf16 v[24:27], v[142:145], v[166:169], v[24:27]
	v_mfma_f32_16x16x32_bf16 v[12:15], v[134:137], v[174:177], v[12:15]
	v_mfma_f32_16x16x32_bf16 v[8:11], v[142:145], v[174:177], v[8:11]
	s_setprio 0
	s_barrier
	s_add_i32 s10, s10, s88
	v_lshl_add_u64 v[130:131], v[202:203], 0, s[62:63]
	s_mov_b32 m0, s10
	s_nop 0
	global_load_lds_dwordx4 v[130:131], off
	v_lshl_add_u64 v[130:131], v[204:205], 0, s[62:63]
	s_add_i32 m0, s10, 0x2000
	s_nop 0
	global_load_lds_dwordx4 v[130:131], off
	s_waitcnt vmcnt(6)
	s_barrier
	s_setprio 1
	v_mfma_f32_16x16x32_bf16 v[70:73], v[178:181], v[146:149], v[70:73]
	v_mfma_f32_16x16x32_bf16 v[60:63], v[186:189], v[146:149], v[60:63]
	v_mfma_f32_16x16x32_bf16 v[36:39], v[178:181], v[154:157], v[36:39]
	v_mfma_f32_16x16x32_bf16 v[32:35], v[186:189], v[154:157], v[32:35]
	v_mfma_f32_16x16x32_bf16 v[20:23], v[178:181], v[162:165], v[20:23]
	v_mfma_f32_16x16x32_bf16 v[16:19], v[186:189], v[162:165], v[16:19]
	v_mfma_f32_16x16x32_bf16 v[4:7], v[178:181], v[170:173], v[4:7]
	v_mfma_f32_16x16x32_bf16 v[0:3], v[186:189], v[170:173], v[0:3]
	v_mfma_f32_16x16x32_bf16 v[70:73], v[182:185], v[150:153], v[70:73]
	v_mfma_f32_16x16x32_bf16 v[60:63], v[190:193], v[150:153], v[60:63]
	v_mfma_f32_16x16x32_bf16 v[36:39], v[182:185], v[158:161], v[36:39]
	v_mfma_f32_16x16x32_bf16 v[32:35], v[190:193], v[158:161], v[32:35]
	v_mfma_f32_16x16x32_bf16 v[20:23], v[182:185], v[166:169], v[20:23]
	v_mfma_f32_16x16x32_bf16 v[16:19], v[190:193], v[166:169], v[16:19]
	v_mfma_f32_16x16x32_bf16 v[4:7], v[182:185], v[174:177], v[4:7]
	v_mfma_f32_16x16x32_bf16 v[0:3], v[190:193], v[174:177], v[0:3]
	s_setprio 0
	s_add_u32 s0, s0, 0x100
	s_addc_u32 s1, s1, 0
	s_add_u32 s14, s14, 0x100
	s_addc_u32 s15, s15, 0
	s_cmp_ge_i32 s22, s46
	s_mov_b32 s10, s22
	s_barrier
	s_cbranch_scc0 .LBB0_372
